# v27 + prologue x RMS-norm: each row's wave sum uses DPP lane movement and permlane16/32 swaps instead of six ds_bpermute round trips
# speedup vs baseline: 1.0089x; 1.0089x over previous
; #define GAS __attribute__((address_space(1)))
; __device__ __forceinline__ unsigned pk2(float lo, float hi) { return pg8::cvt_pk_bf16(lo, hi); }
; __device__ __forceinline__ float wave_sum(float v) {
; #pragma unroll
;     for (int o = 1; o < 64; o <<= 1) v += __shfl_xor(v, o);
;     return v;
; __device__ __forceinline__ void p0_prologue(KArgs A, unsigned char* ws, LAS unsigned char* lds, int vcu, int G, int wave, int lane) {
;     ...
;     for (int m = gw; m < MALL; m += 4 * NGW) {
;         f32x4 v[4][4]; int mr[4]; bool has[4];
; #pragma unroll
;         for (int r = 0; r < 4; ++r) { const int mm = m + r * NGW; has[r] = mm < MALL; mr[r] = has[r] ? mm : m;
;             const float* xr = mr[r] < MP ? A->in.xp + (size_t)mr[r] * DM : A->in.xs + (size_t)(mr[r] - MP) * DM; const GAS f32x4* p = (const GAS f32x4*)xr + lane;
; #pragma unroll
;             for (int j = 0; j < 4; ++j) v[r][j] = p[64 * j]; }
; #pragma unroll
;         for (int r = 0; r < 4; ++r) { float s = 0.f;
; #pragma unroll
;             for (int j = 0; j < 4; ++j) s += (v[r][j][0] * v[r][j][0] + v[r][j][1] * v[r][j][1]) + (v[r][j][2] * v[r][j][2] + v[r][j][3] * v[r][j][3]);
;             s = wave_sum(s);
;             const float rs = rsqrtf(s * (1.0f / DM) + EPSF);
;             if (has[r]) { GAS v2u* o = (GAS v2u*)(XB + (size_t)mr[r] * DM) + lane;
; #pragma unroll
;                 for (int j = 0; j < 4; ++j) o[64 * j] = (v2u){pk2(v[r][j][0] * rs, v[r][j][1] * rs), pk2(v[r][j][2] * rs, v[r][j][3] * rs)};
;                 if (lane == 0) { RSTD1[mr[r]] = 1.0f / rs; RSS[mr[r]] = 0.f; } }
.LBB0_87:
	s_add_i32 s8, s14, 0xffffc000
	s_ashr_i32 s15, s14, 31
	s_cmpk_lt_i32 s14, 0x4000
	s_cselect_b32 s10, s98, s100
	s_cselect_b32 s11, s99, s101
	s_cselect_b32 s9, s15, 0
	s_cselect_b32 s8, s14, s8
	s_lshl_b64 s[8:9], s[8:9], 12
	s_waitcnt lgkmcnt(0)
	s_add_u32 s8, s10, s8
	s_addc_u32 s9, s11, s9
	global_load_dwordx4 v[58:61], v75, s[8:9]
	global_load_dwordx4 v[54:57], v75, s[8:9] offset:1024
	global_load_dwordx4 v[46:49], v75, s[8:9] offset:3072
	global_load_dwordx4 v[62:65], v75, s[8:9] offset:2048
	s_add_i32 s16, s0, s14
	s_cmpk_lt_i32 s16, 0x4200
	s_cselect_b64 s[18:19], -1, 0
	s_and_b64 s[8:9], s[18:19], exec
	s_cselect_b32 s8, s16, s14
	s_ashr_i32 s9, s8, 31
	s_add_i32 s10, s8, 0xffffc000
	s_cmpk_lt_i32 s8, 0x4000
	s_cselect_b32 s8, s8, s10
	s_cselect_b32 s10, s98, s100
	s_cselect_b32 s11, s99, s101
	s_cselect_b32 s9, s9, 0
	s_lshl_b64 s[8:9], s[8:9], 12
	s_waitcnt lgkmcnt(0)
	s_add_u32 s8, s10, s8
	s_addc_u32 s9, s11, s9
	s_add_i32 s17, s0, s16
	s_cmpk_lt_i32 s17, 0x4200
	s_cselect_b64 s[10:11], -1, 0
	s_and_b64 s[20:21], s[10:11], exec
	s_cselect_b32 s20, s17, s14
	s_ashr_i32 s21, s20, 31
	s_add_i32 s22, s20, 0xffffc000
	s_cmpk_lt_i32 s20, 0x4000
	s_cselect_b32 s20, s20, s22
	s_cselect_b32 s22, s98, s100
	s_cselect_b32 s23, s99, s101
	s_cselect_b32 s21, s21, 0
	global_load_dwordx4 v[38:41], v75, s[8:9]
	global_load_dwordx4 v[34:37], v75, s[8:9] offset:1024
	global_load_dwordx4 v[50:53], v75, s[8:9] offset:2048
	global_load_dwordx4 v[42:45], v75, s[8:9] offset:3072
	s_lshl_b64 s[8:9], s[20:21], 12
	s_waitcnt lgkmcnt(0)
	s_add_u32 s20, s22, s8
	s_addc_u32 s21, s23, s9
	s_add_i32 s22, s0, s17
	s_cmpk_lt_i32 s22, 0x4200
	s_cselect_b64 s[8:9], -1, 0
	s_and_b64 s[28:29], s[8:9], exec
	s_cselect_b32 s17, s22, s14
	s_ashr_i32 s23, s17, 31
	s_add_i32 s28, s17, 0xffffc000
	s_cmpk_lt_i32 s17, 0x4000
	s_cselect_b32 s28, s17, s28
	s_cselect_b32 s30, s98, s100
	s_cselect_b32 s31, s99, s101
	s_cselect_b32 s29, s23, 0
	global_load_dwordx4 v[30:33], v75, s[20:21]
	global_load_dwordx4 v[26:29], v75, s[20:21] offset:1024
	global_load_dwordx4 v[22:25], v75, s[20:21] offset:2048
	global_load_dwordx4 v[18:21], v75, s[20:21] offset:3072
	s_lshl_b64 s[20:21], s[28:29], 12
	s_waitcnt lgkmcnt(0)
	s_add_u32 s20, s30, s20
	s_addc_u32 s21, s31, s21
	global_load_dwordx4 v[6:9], v75, s[20:21]
	global_load_dwordx4 v[2:5], v75, s[20:21] offset:1024
	global_load_dwordx4 v[14:17], v75, s[20:21] offset:2048
	global_load_dwordx4 v[10:13], v75, s[20:21] offset:3072
	s_lshl_b64 s[20:21], s[14:15], 11
	s_waitcnt vmcnt(15)
	v_pk_mul_f32 v[78:79], v[60:61], v[60:61]
	v_pk_mul_f32 v[80:81], v[58:59], v[58:59]
	s_waitcnt vmcnt(14)
	v_pk_mul_f32 v[82:83], v[56:57], v[56:57]
	v_pk_mul_f32 v[84:85], v[54:55], v[54:55]
	v_pk_mov_b32 v[88:89], v[80:81], v[78:79] op_sel:[1,0]
	v_mov_b32_e32 v81, v79
	v_pk_mov_b32 v[78:79], v[84:85], v[82:83] op_sel:[1,0]
	v_mov_b32_e32 v85, v83
	s_waitcnt vmcnt(12)
	v_mul_f32_e32 v66, v63, v63
	v_mul_f32_e32 v86, v65, v65
	v_pk_add_f32 v[80:81], v[88:89], v[80:81]
	v_pk_add_f32 v[78:79], v[78:79], v[84:85]
	v_mul_f32_e32 v77, v46, v46
	v_mul_f32_e32 v90, v47, v47
	v_mul_f32_e32 v91, v48, v48
	v_mul_f32_e32 v92, v49, v49
	v_pk_fma_f32 v[82:83], v[62:63], v[62:63], v[66:67] op_sel_hi:[1,1,0]
	v_pk_fma_f32 v[86:87], v[64:65], v[64:65], v[86:87] op_sel_hi:[1,1,0]
	v_pk_add_f32 v[80:81], v[80:81], v[80:81] op_sel:[0,1] op_sel_hi:[1,0]
	v_pk_add_f32 v[78:79], v[78:79], v[78:79] op_sel:[0,1] op_sel_hi:[1,0]
	v_mov_b32_e32 v83, v91
	v_mov_b32_e32 v87, v92
	v_mov_b32_e32 v81, v77
	v_mov_b32_e32 v79, v90
	v_pk_add_f32 v[82:83], v[82:83], v[86:87]
	v_pk_add_f32 v[78:79], v[80:81], v[78:79]
	s_nop 0
	v_pk_add_f32 v[78:79], v[78:79], v[82:83]
	s_nop 0
	v_add_f32_e32 v66, v78, v79
	s_nop 1
	v_mov_b32_dpp v77, v66 quad_perm:[1,0,3,2] row_mask:0xf bank_mask:0xf
	v_lshl_add_u64 v[78:79], v[68:69], 0, s[20:21]
	s_waitcnt lgkmcnt(0)
	v_add_f32_e32 v66, v66, v77
	s_nop 1
	v_mov_b32_dpp v77, v66 quad_perm:[2,3,0,1] row_mask:0xf bank_mask:0xf
	s_waitcnt lgkmcnt(0)
	v_add_f32_e32 v66, v66, v77
	s_nop 1
	v_mov_b32_dpp v77, v66 row_shr:4 row_mask:0xf bank_mask:0xa
	v_mov_b32_dpp v77, v66 row_shl:4 row_mask:0xf bank_mask:0x5
	s_waitcnt lgkmcnt(0)
	v_add_f32_e32 v66, v66, v77
	s_nop 1
	v_mov_b32_dpp v77, v66 row_ror:8 row_mask:0xf bank_mask:0xf
	s_waitcnt lgkmcnt(0)
	v_add_f32_e32 v66, v66, v77
	v_mov_b32_e32 v77, v66
	s_nop 1
	v_permlane16_swap_b32_e32 v77, v66
	s_waitcnt lgkmcnt(0)
	v_add_f32_e32 v66, v66, v77
	v_mov_b32_e32 v77, v66
	s_nop 1
	v_permlane32_swap_b32_e32 v77, v66
	s_waitcnt lgkmcnt(0)
	v_add_f32_e32 v66, v66, v77
	v_fmamk_f32 v66, v66, 0x3a800000, v76
	v_mul_f32_e32 v77, 0x4b800000, v66
	v_cmp_gt_f32_e32 vcc, s27, v66
	s_nop 1
	v_cndmask_b32_e32 v66, v66, v77, vcc
	v_rsq_f32_e32 v66, v66
	s_nop 0
	v_mul_f32_e32 v77, 0x45800000, v66
	v_cndmask_b32_e32 v66, v66, v77, vcc
	v_pk_mul_f32 v[58:59], v[58:59], v[66:67] op_sel_hi:[1,0]
	v_pk_mul_f32 v[60:61], v[60:61], v[66:67] op_sel_hi:[1,0]
	v_pk_mul_f32 v[54:55], v[54:55], v[66:67] op_sel_hi:[1,0]
	v_pk_mul_f32 v[56:57], v[56:57], v[66:67] op_sel_hi:[1,0]
	v_pk_mul_f32 v[62:63], v[62:63], v[66:67] op_sel_hi:[1,0]
	v_pk_mul_f32 v[64:65], v[64:65], v[66:67] op_sel_hi:[1,0]
	v_pk_mul_f32 v[46:47], v[46:47], v[66:67] op_sel_hi:[1,0]
	v_pk_mul_f32 v[48:49], v[48:49], v[66:67] op_sel_hi:[1,0]
	v_cvt_pk_bf16_f32 v58, v58, v59
	v_cvt_pk_bf16_f32 v59, v60, v61
	v_cvt_pk_bf16_f32 v54, v54, v55
	v_cvt_pk_bf16_f32 v55, v56, v57
	v_cvt_pk_bf16_f32 v56, v62, v63
	v_cvt_pk_bf16_f32 v57, v64, v65
	v_cvt_pk_bf16_f32 v46, v46, v47
	v_cvt_pk_bf16_f32 v47, v48, v49
	global_store_dwordx2 v[78:79], v[58:59], off
	global_store_dwordx2 v[78:79], v[54:55], off offset:512
	global_store_dwordx2 v[78:79], v[56:57], off offset:1024
	global_store_dwordx2 v[78:79], v[46:47], off offset:1536
	s_and_saveexec_b64 s[20:21], s[6:7]
	s_cbranch_execz .LBB0_89
	v_div_scale_f32 v46, s[28:29], v66, v66, 1.0
	v_rcp_f32_e32 v47, v46
	v_div_scale_f32 v48, vcc, 1.0, v66, 1.0
	s_lshl_b64 s[28:29], s[14:15], 2
	v_fma_f32 v49, -v46, v47, 1.0
	v_fmac_f32_e32 v47, v49, v47
	v_mul_f32_e32 v49, v48, v47
	v_fma_f32 v54, -v46, v49, v48
	v_fmac_f32_e32 v49, v54, v47
	s_add_u32 s30, s1, s28
	v_fma_f32 v46, -v46, v49, v48
	s_addc_u32 s31, s2, s29
	v_div_fmas_f32 v46, v46, v47, v49
	s_add_u32 s28, s3, s28
	v_div_fixup_f32 v46, v46, v66, 1.0
	s_addc_u32 s29, s24, s29
	global_store_dword v67, v46, s[30:31]
	global_store_dword v67, v67, s[28:29]
; #define GAS __attribute__((address_space(1)))
; __device__ __forceinline__ unsigned pk2(float lo, float hi) { return pg8::cvt_pk_bf16(lo, hi); }
; __device__ __forceinline__ float wave_sum(float v) {
; #pragma unroll
;     for (int o = 1; o < 64; o <<= 1) v += __shfl_xor(v, o);
;     return v;
; __device__ __forceinline__ void p0_prologue(KArgs A, unsigned char* ws, LAS unsigned char* lds, int vcu, int G, int wave, int lane) {
;     ...
;         for (int r = 0; r < 4; ++r) { float s = 0.f;
; #pragma unroll
;             for (int j = 0; j < 4; ++j) s += (v[r][j][0] * v[r][j][0] + v[r][j][1] * v[r][j][1]) + (v[r][j][2] * v[r][j][2] + v[r][j][3] * v[r][j][3]);
;             s = wave_sum(s);
;             const float rs = rsqrtf(s * (1.0f / DM) + EPSF);
;             if (has[r]) { GAS v2u* o = (GAS v2u*)(XB + (size_t)mr[r] * DM) + lane;
; #pragma unroll
;                 for (int j = 0; j < 4; ++j) o[64 * j] = (v2u){pk2(v[r][j][0] * rs, v[r][j][1] * rs), pk2(v[r][j][2] * rs, v[r][j][3] * rs)};
;                 if (lane == 0) { RSTD1[mr[r]] = 1.0f / rs; RSS[mr[r]] = 0.f; } }
.LBB0_89:
	s_or_b64 exec, exec, s[20:21]
	s_waitcnt vmcnt(15)
	v_pk_mul_f32 v[46:47], v[40:41], v[40:41]
	v_pk_mul_f32 v[48:49], v[38:39], v[38:39]
	s_andn2_b64 vcc, exec, s[18:19]
	v_pk_mov_b32 v[54:55], v[48:49], v[46:47] op_sel:[1,0]
	v_mov_b32_e32 v49, v47
	v_pk_add_f32 v[46:47], v[54:55], v[48:49]
	s_waitcnt vmcnt(14)
	v_pk_mul_f32 v[48:49], v[36:37], v[36:37]
	v_pk_mul_f32 v[54:55], v[34:35], v[34:35]
	v_pk_add_f32 v[46:47], v[46:47], v[46:47] op_sel:[0,1] op_sel_hi:[1,0]
	v_pk_mov_b32 v[56:57], v[54:55], v[48:49] op_sel:[1,0]
	v_mov_b32_e32 v55, v49
	v_pk_add_f32 v[48:49], v[56:57], v[54:55]
	s_waitcnt vmcnt(12)
	v_mul_f32_e32 v54, v42, v42
	v_mul_f32_e32 v55, v43, v43
	v_pk_add_f32 v[48:49], v[48:49], v[48:49] op_sel:[0,1] op_sel_hi:[1,0]
	v_mov_b32_e32 v47, v54
	v_mov_b32_e32 v49, v55
	v_pk_add_f32 v[46:47], v[46:47], v[48:49]
	v_mul_f32_e32 v48, v51, v51
	v_mul_f32_e32 v54, v53, v53
	v_mul_f32_e32 v56, v44, v44
	v_mul_f32_e32 v57, v45, v45
	v_pk_fma_f32 v[48:49], v[50:51], v[50:51], v[48:49] op_sel_hi:[1,1,0]
	v_pk_fma_f32 v[54:55], v[52:53], v[52:53], v[54:55] op_sel_hi:[1,1,0]
	v_mov_b32_e32 v49, v56
	v_mov_b32_e32 v55, v57
	v_pk_add_f32 v[48:49], v[48:49], v[54:55]
	s_nop 0
	v_pk_add_f32 v[46:47], v[46:47], v[48:49]
	s_nop 0
	v_add_f32_e32 v46, v46, v47
	s_nop 1
	v_mov_b32_dpp v47, v46 quad_perm:[1,0,3,2] row_mask:0xf bank_mask:0xf
	s_waitcnt lgkmcnt(0)
	v_add_f32_e32 v46, v46, v47
	s_nop 1
	v_mov_b32_dpp v47, v46 quad_perm:[2,3,0,1] row_mask:0xf bank_mask:0xf
	s_waitcnt lgkmcnt(0)
	v_add_f32_e32 v46, v46, v47
	s_nop 1
	v_mov_b32_dpp v47, v46 row_shr:4 row_mask:0xf bank_mask:0xa
	v_mov_b32_dpp v47, v46 row_shl:4 row_mask:0xf bank_mask:0x5
	s_waitcnt lgkmcnt(0)
	v_add_f32_e32 v46, v46, v47
	s_nop 1
	v_mov_b32_dpp v47, v46 row_ror:8 row_mask:0xf bank_mask:0xf
	s_waitcnt lgkmcnt(0)
	v_add_f32_e32 v46, v46, v47
	v_mov_b32_e32 v47, v46
	s_nop 1
	v_permlane16_swap_b32_e32 v47, v46
	s_waitcnt lgkmcnt(0)
	v_add_f32_e32 v46, v46, v47
	v_mov_b32_e32 v47, v46
	s_nop 1
	v_permlane32_swap_b32_e32 v47, v46
	s_cbranch_vccnz .LBB0_93
	s_waitcnt lgkmcnt(0)
	v_add_f32_e32 v46, v46, v47
	v_fmamk_f32 v46, v46, 0x3a800000, v76
	v_mul_f32_e32 v47, 0x4b800000, v46
	v_cmp_gt_f32_e32 vcc, s27, v46
	s_ashr_i32 s17, s16, 31
	s_lshl_b64 s[18:19], s[16:17], 11
	v_cndmask_b32_e32 v46, v46, v47, vcc
	v_rsq_f32_e32 v46, v46
	v_lshl_add_u64 v[48:49], v[68:69], 0, s[18:19]
	v_mul_f32_e32 v47, 0x45800000, v46
	v_cndmask_b32_e32 v46, v46, v47, vcc
	v_pk_mul_f32 v[34:35], v[34:35], v[46:47] op_sel_hi:[1,0]
	v_pk_mul_f32 v[36:37], v[36:37], v[46:47] op_sel_hi:[1,0]
	v_cvt_pk_bf16_f32 v34, v34, v35
	v_cvt_pk_bf16_f32 v35, v36, v37
	global_store_dwordx2 v[48:49], v[34:35], off offset:512
	v_pk_mul_f32 v[34:35], v[50:51], v[46:47] op_sel_hi:[1,0]
	v_pk_mul_f32 v[36:37], v[52:53], v[46:47] op_sel_hi:[1,0]
	v_cvt_pk_bf16_f32 v34, v34, v35
	v_cvt_pk_bf16_f32 v35, v36, v37
	v_pk_mul_f32 v[38:39], v[38:39], v[46:47] op_sel_hi:[1,0]
	v_pk_mul_f32 v[40:41], v[40:41], v[46:47] op_sel_hi:[1,0]
	global_store_dwordx2 v[48:49], v[34:35], off offset:1024
	v_pk_mul_f32 v[34:35], v[42:43], v[46:47] op_sel_hi:[1,0]
	v_pk_mul_f32 v[36:37], v[44:45], v[46:47] op_sel_hi:[1,0]
	v_cvt_pk_bf16_f32 v38, v38, v39
	v_cvt_pk_bf16_f32 v39, v40, v41
	v_cvt_pk_bf16_f32 v34, v34, v35
	v_cvt_pk_bf16_f32 v35, v36, v37
	global_store_dwordx2 v[48:49], v[38:39], off
	global_store_dwordx2 v[48:49], v[34:35], off offset:1536
	s_and_saveexec_b64 s[18:19], s[6:7]
	s_cbranch_execz .LBB0_92
	v_div_scale_f32 v34, s[20:21], v46, v46, 1.0
	v_rcp_f32_e32 v35, v34
	v_div_scale_f32 v36, vcc, 1.0, v46, 1.0
	s_lshl_b64 s[16:17], s[16:17], 2
	v_fma_f32 v37, -v34, v35, 1.0
	v_fmac_f32_e32 v35, v37, v35
	v_mul_f32_e32 v37, v36, v35
	v_fma_f32 v38, -v34, v37, v36
	v_fmac_f32_e32 v37, v38, v35
	s_add_u32 s20, s1, s16
	v_fma_f32 v34, -v34, v37, v36
	s_addc_u32 s21, s2, s17
	v_div_fmas_f32 v34, v34, v35, v37
	s_add_u32 s16, s3, s16
	v_div_fixup_f32 v34, v34, v46, 1.0
	s_addc_u32 s17, s24, s17
	global_store_dword v67, v34, s[20:21]
	global_store_dword v67, v67, s[16:17]

; #define GAS __attribute__((address_space(1)))
; __device__ __forceinline__ unsigned pk2(float lo, float hi) { return pg8::cvt_pk_bf16(lo, hi); }
; __device__ __forceinline__ float wave_sum(float v) {
; #pragma unroll
;     for (int o = 1; o < 64; o <<= 1) v += __shfl_xor(v, o);
;     return v;
; __device__ __forceinline__ void p0_prologue(KArgs A, unsigned char* ws, LAS unsigned char* lds, int vcu, int G, int wave, int lane) {
;     ...
;         for (int r = 0; r < 4; ++r) { float s = 0.f;
; #pragma unroll
;             for (int j = 0; j < 4; ++j) s += (v[r][j][0] * v[r][j][0] + v[r][j][1] * v[r][j][1]) + (v[r][j][2] * v[r][j][2] + v[r][j][3] * v[r][j][3]);
;             s = wave_sum(s);
;             const float rs = rsqrtf(s * (1.0f / DM) + EPSF);
;             if (has[r]) { GAS v2u* o = (GAS v2u*)(XB + (size_t)mr[r] * DM) + lane;
; #pragma unroll
;                 for (int j = 0; j < 4; ++j) o[64 * j] = (v2u){pk2(v[r][j][0] * rs, v[r][j][1] * rs), pk2(v[r][j][2] * rs, v[r][j][3] * rs)};
;                 if (lane == 0) { RSTD1[mr[r]] = 1.0f / rs; RSS[mr[r]] = 0.f; } }
.LBB0_93:
	s_waitcnt vmcnt(11)
	v_pk_mul_f32 v[34:35], v[32:33], v[32:33]
	v_pk_mul_f32 v[36:37], v[30:31], v[30:31]
	s_andn2_b64 vcc, exec, s[10:11]
	v_pk_mov_b32 v[38:39], v[36:37], v[34:35] op_sel:[1,0]
	v_mov_b32_e32 v37, v35
	v_pk_add_f32 v[34:35], v[38:39], v[36:37]
	s_waitcnt vmcnt(10)
	v_pk_mul_f32 v[36:37], v[28:29], v[28:29]
	v_pk_mul_f32 v[38:39], v[26:27], v[26:27]
	v_pk_add_f32 v[34:35], v[34:35], v[34:35] op_sel:[0,1] op_sel_hi:[1,0]
	v_pk_mov_b32 v[40:41], v[38:39], v[36:37] op_sel:[1,0]
	v_mov_b32_e32 v39, v37
	v_pk_add_f32 v[36:37], v[40:41], v[38:39]
	s_waitcnt vmcnt(8)
	v_mul_f32_e32 v38, v18, v18
	v_mul_f32_e32 v39, v19, v19
	v_pk_add_f32 v[36:37], v[36:37], v[36:37] op_sel:[0,1] op_sel_hi:[1,0]
	v_mov_b32_e32 v35, v38
	v_mov_b32_e32 v37, v39
	v_pk_add_f32 v[34:35], v[34:35], v[36:37]
	v_mul_f32_e32 v36, v23, v23
	v_mul_f32_e32 v38, v25, v25
	v_mul_f32_e32 v40, v20, v20
	v_mul_f32_e32 v41, v21, v21
	v_pk_fma_f32 v[36:37], v[22:23], v[22:23], v[36:37] op_sel_hi:[1,1,0]
	v_pk_fma_f32 v[38:39], v[24:25], v[24:25], v[38:39] op_sel_hi:[1,1,0]
	v_mov_b32_e32 v37, v40
	v_mov_b32_e32 v39, v41
	v_pk_add_f32 v[36:37], v[36:37], v[38:39]
	s_nop 0
	v_pk_add_f32 v[34:35], v[34:35], v[36:37]
	s_nop 0
	v_add_f32_e32 v34, v34, v35
	s_nop 1
	v_mov_b32_dpp v35, v34 quad_perm:[1,0,3,2] row_mask:0xf bank_mask:0xf
	s_waitcnt lgkmcnt(0)
	v_add_f32_e32 v34, v34, v35
	s_nop 1
	v_mov_b32_dpp v35, v34 quad_perm:[2,3,0,1] row_mask:0xf bank_mask:0xf
	s_waitcnt lgkmcnt(0)
	v_add_f32_e32 v34, v34, v35
	s_nop 1
	v_mov_b32_dpp v35, v34 row_shr:4 row_mask:0xf bank_mask:0xa
	v_mov_b32_dpp v35, v34 row_shl:4 row_mask:0xf bank_mask:0x5
	s_waitcnt lgkmcnt(0)
	v_add_f32_e32 v34, v34, v35
	s_nop 1
	v_mov_b32_dpp v35, v34 row_ror:8 row_mask:0xf bank_mask:0xf
	s_waitcnt lgkmcnt(0)
	v_add_f32_e32 v34, v34, v35
	v_mov_b32_e32 v35, v34
	s_nop 1
	v_permlane16_swap_b32_e32 v35, v34
	s_waitcnt lgkmcnt(0)
	v_add_f32_e32 v34, v34, v35
	v_mov_b32_e32 v35, v34
	s_nop 1
	v_permlane32_swap_b32_e32 v35, v34
	s_cbranch_vccnz .LBB0_97
	s_waitcnt lgkmcnt(0)
	v_add_f32_e32 v34, v34, v35
	v_fmamk_f32 v34, v34, 0x3a800000, v76
	v_mul_f32_e32 v35, 0x4b800000, v34
	v_cmp_gt_f32_e32 vcc, s27, v34
	s_add_i32 s10, s25, s14
	s_ashr_i32 s11, s10, 31
	v_cndmask_b32_e32 v34, v34, v35, vcc
	v_rsq_f32_e32 v34, v34
	s_lshl_b64 s[16:17], s[10:11], 11
	v_lshl_add_u64 v[36:37], v[68:69], 0, s[16:17]
	v_mul_f32_e32 v35, 0x45800000, v34
	v_cndmask_b32_e32 v34, v34, v35, vcc
	v_pk_mul_f32 v[30:31], v[30:31], v[34:35] op_sel_hi:[1,0]
	v_pk_mul_f32 v[32:33], v[32:33], v[34:35] op_sel_hi:[1,0]
	v_pk_mul_f32 v[26:27], v[26:27], v[34:35] op_sel_hi:[1,0]
	v_pk_mul_f32 v[28:29], v[28:29], v[34:35] op_sel_hi:[1,0]
	v_pk_mul_f32 v[22:23], v[22:23], v[34:35] op_sel_hi:[1,0]
	v_pk_mul_f32 v[24:25], v[24:25], v[34:35] op_sel_hi:[1,0]
	v_pk_mul_f32 v[18:19], v[18:19], v[34:35] op_sel_hi:[1,0]
	v_pk_mul_f32 v[20:21], v[20:21], v[34:35] op_sel_hi:[1,0]
	v_cvt_pk_bf16_f32 v30, v30, v31
	v_cvt_pk_bf16_f32 v31, v32, v33
	v_cvt_pk_bf16_f32 v26, v26, v27
	v_cvt_pk_bf16_f32 v27, v28, v29
	v_cvt_pk_bf16_f32 v22, v22, v23
	v_cvt_pk_bf16_f32 v23, v24, v25
	v_cvt_pk_bf16_f32 v18, v18, v19
	v_cvt_pk_bf16_f32 v19, v20, v21
	global_store_dwordx2 v[36:37], v[30:31], off
	global_store_dwordx2 v[36:37], v[26:27], off offset:512
	global_store_dwordx2 v[36:37], v[22:23], off offset:1024
	global_store_dwordx2 v[36:37], v[18:19], off offset:1536
	s_and_saveexec_b64 s[16:17], s[6:7]
	s_cbranch_execz .LBB0_96
	v_div_scale_f32 v18, s[18:19], v34, v34, 1.0
	v_rcp_f32_e32 v19, v18
	v_div_scale_f32 v20, vcc, 1.0, v34, 1.0
	s_lshl_b64 s[10:11], s[10:11], 2
	v_fma_f32 v21, -v18, v19, 1.0
	v_fmac_f32_e32 v19, v21, v19
	v_mul_f32_e32 v21, v20, v19
	v_fma_f32 v22, -v18, v21, v20
	v_fmac_f32_e32 v21, v22, v19
	s_add_u32 s18, s1, s10
	v_fma_f32 v18, -v18, v21, v20
	s_addc_u32 s19, s2, s11
	v_div_fmas_f32 v18, v18, v19, v21
	s_add_u32 s10, s3, s10
	v_div_fixup_f32 v18, v18, v34, 1.0
	s_addc_u32 s11, s24, s11
	global_store_dword v67, v18, s[18:19]
	global_store_dword v67, v67, s[10:11]

; #define GAS __attribute__((address_space(1)))
; __device__ __forceinline__ unsigned pk2(float lo, float hi) { return pg8::cvt_pk_bf16(lo, hi); }
; __device__ __forceinline__ float wave_sum(float v) {
; #pragma unroll
;     for (int o = 1; o < 64; o <<= 1) v += __shfl_xor(v, o);
;     return v;
; __device__ __forceinline__ void p0_prologue(KArgs A, unsigned char* ws, LAS unsigned char* lds, int vcu, int G, int wave, int lane) {
;     ...
;         for (int r = 0; r < 4; ++r) { float s = 0.f;
; #pragma unroll
;             for (int j = 0; j < 4; ++j) s += (v[r][j][0] * v[r][j][0] + v[r][j][1] * v[r][j][1]) + (v[r][j][2] * v[r][j][2] + v[r][j][3] * v[r][j][3]);
;             s = wave_sum(s);
;             const float rs = rsqrtf(s * (1.0f / DM) + EPSF);
;             if (has[r]) { GAS v2u* o = (GAS v2u*)(XB + (size_t)mr[r] * DM) + lane;
; #pragma unroll
;                 for (int j = 0; j < 4; ++j) o[64 * j] = (v2u){pk2(v[r][j][0] * rs, v[r][j][1] * rs), pk2(v[r][j][2] * rs, v[r][j][3] * rs)};
;                 if (lane == 0) { RSTD1[mr[r]] = 1.0f / rs; RSS[mr[r]] = 0.f; } }
.LBB0_97:
	s_waitcnt vmcnt(7)
	v_pk_mul_f32 v[18:19], v[8:9], v[8:9]
	v_pk_mul_f32 v[20:21], v[6:7], v[6:7]
	s_andn2_b64 vcc, exec, s[8:9]
	v_pk_mov_b32 v[22:23], v[20:21], v[18:19] op_sel:[1,0]
	v_mov_b32_e32 v21, v19
	v_pk_add_f32 v[18:19], v[22:23], v[20:21]
	s_waitcnt vmcnt(6)
	v_pk_mul_f32 v[20:21], v[4:5], v[4:5]
	v_pk_mul_f32 v[22:23], v[2:3], v[2:3]
	v_pk_add_f32 v[18:19], v[18:19], v[18:19] op_sel:[0,1] op_sel_hi:[1,0]
	v_pk_mov_b32 v[24:25], v[22:23], v[20:21] op_sel:[1,0]
	v_mov_b32_e32 v23, v21
	v_pk_add_f32 v[20:21], v[24:25], v[22:23]
	s_waitcnt vmcnt(4)
	v_mul_f32_e32 v22, v10, v10
	v_mul_f32_e32 v23, v11, v11
	v_pk_add_f32 v[20:21], v[20:21], v[20:21] op_sel:[0,1] op_sel_hi:[1,0]
	v_mov_b32_e32 v19, v22
	v_mov_b32_e32 v21, v23
	v_pk_add_f32 v[18:19], v[18:19], v[20:21]
	v_mul_f32_e32 v20, v15, v15
	v_mul_f32_e32 v22, v17, v17
	v_mul_f32_e32 v24, v12, v12
	v_mul_f32_e32 v25, v13, v13
	v_pk_fma_f32 v[20:21], v[14:15], v[14:15], v[20:21] op_sel_hi:[1,1,0]
	v_pk_fma_f32 v[22:23], v[16:17], v[16:17], v[22:23] op_sel_hi:[1,1,0]
	v_mov_b32_e32 v21, v24
	v_mov_b32_e32 v23, v25
	v_pk_add_f32 v[20:21], v[20:21], v[22:23]
	s_nop 0
	v_pk_add_f32 v[18:19], v[18:19], v[20:21]
	s_nop 0
	v_add_f32_e32 v18, v18, v19
	s_nop 1
	v_mov_b32_dpp v19, v18 quad_perm:[1,0,3,2] row_mask:0xf bank_mask:0xf
	s_waitcnt lgkmcnt(0)
	v_add_f32_e32 v18, v18, v19
	s_nop 1
	v_mov_b32_dpp v19, v18 quad_perm:[2,3,0,1] row_mask:0xf bank_mask:0xf
	s_waitcnt lgkmcnt(0)
	v_add_f32_e32 v18, v18, v19
	s_nop 1
	v_mov_b32_dpp v19, v18 row_shr:4 row_mask:0xf bank_mask:0xa
	v_mov_b32_dpp v19, v18 row_shl:4 row_mask:0xf bank_mask:0x5
	s_waitcnt lgkmcnt(0)
	v_add_f32_e32 v18, v18, v19
	s_nop 1
	v_mov_b32_dpp v19, v18 row_ror:8 row_mask:0xf bank_mask:0xf
	s_waitcnt lgkmcnt(0)
	v_add_f32_e32 v18, v18, v19
	v_mov_b32_e32 v19, v18
	s_nop 1
	v_permlane16_swap_b32_e32 v19, v18
	s_waitcnt lgkmcnt(0)
	v_add_f32_e32 v18, v18, v19
	v_mov_b32_e32 v19, v18
	s_nop 1
	v_permlane32_swap_b32_e32 v19, v18
	s_cbranch_vccnz .LBB0_86
	s_waitcnt lgkmcnt(0)
	v_add_f32_e32 v18, v18, v19
	v_fmamk_f32 v18, v18, 0x3a800000, v76
	v_mul_f32_e32 v19, 0x4b800000, v18
	v_cmp_gt_f32_e32 vcc, s27, v18
	s_add_i32 s8, s26, s14
	s_ashr_i32 s9, s8, 31
	v_cndmask_b32_e32 v18, v18, v19, vcc
	v_rsq_f32_e32 v18, v18
	s_lshl_b64 s[10:11], s[8:9], 11
	v_lshl_add_u64 v[20:21], v[68:69], 0, s[10:11]
	v_mul_f32_e32 v19, 0x45800000, v18
	v_cndmask_b32_e32 v18, v18, v19, vcc
	v_pk_mul_f32 v[2:3], v[2:3], v[18:19] op_sel_hi:[1,0]
	v_pk_mul_f32 v[4:5], v[4:5], v[18:19] op_sel_hi:[1,0]
	v_cvt_pk_bf16_f32 v2, v2, v3
	v_cvt_pk_bf16_f32 v3, v4, v5
	global_store_dwordx2 v[20:21], v[2:3], off offset:512
	v_pk_mul_f32 v[2:3], v[14:15], v[18:19] op_sel_hi:[1,0]
	v_pk_mul_f32 v[4:5], v[16:17], v[18:19] op_sel_hi:[1,0]
	v_cvt_pk_bf16_f32 v2, v2, v3
	v_cvt_pk_bf16_f32 v3, v4, v5
	v_pk_mul_f32 v[6:7], v[6:7], v[18:19] op_sel_hi:[1,0]
	v_pk_mul_f32 v[8:9], v[8:9], v[18:19] op_sel_hi:[1,0]
	global_store_dwordx2 v[20:21], v[2:3], off offset:1024
	v_pk_mul_f32 v[2:3], v[10:11], v[18:19] op_sel_hi:[1,0]
	v_pk_mul_f32 v[4:5], v[12:13], v[18:19] op_sel_hi:[1,0]
	v_cvt_pk_bf16_f32 v6, v6, v7
	v_cvt_pk_bf16_f32 v7, v8, v9
	v_cvt_pk_bf16_f32 v2, v2, v3
	v_cvt_pk_bf16_f32 v3, v4, v5
	global_store_dwordx2 v[20:21], v[6:7], off
	global_store_dwordx2 v[20:21], v[2:3], off offset:1536
	s_and_saveexec_b64 s[10:11], s[6:7]
	s_cbranch_execz .LBB0_85
	v_div_scale_f32 v2, s[14:15], v18, v18, 1.0
	v_rcp_f32_e32 v3, v2
	v_div_scale_f32 v4, vcc, 1.0, v18, 1.0
	s_lshl_b64 s[8:9], s[8:9], 2
	v_fma_f32 v5, -v2, v3, 1.0
	v_fmac_f32_e32 v3, v5, v3
	v_mul_f32_e32 v5, v4, v3
	v_fma_f32 v6, -v2, v5, v4
	v_fmac_f32_e32 v5, v6, v3
	s_add_u32 s14, s1, s8
	v_fma_f32 v2, -v2, v5, v4
	s_addc_u32 s15, s2, s9
	v_div_fmas_f32 v2, v2, v3, v5
	s_add_u32 s8, s3, s8
	v_div_fixup_f32 v2, v2, v18, 1.0
	s_addc_u32 s9, s24, s9
	global_store_dword v67, v2, s[14:15]
	global_store_dword v67, v67, s[8:9]
	s_branch .LBB0_85
